# stack4 + GEMM1 K-loop: 16 ds_read_b128 address adds per iteration folded into offset:N immediates off one extra base VGPR
# baseline (speedup 1.0000x reference)
; #define PG8_STAGE(bufoff, gbase, voff) do { _Pragma("unroll") for (int _i = 0; _i < 2; ++_i) \
;         __builtin_amdgcn_global_load_lds((const unsigned*)((const char*)(gbase) + (voff)[_i]), (PG8_LAS unsigned*)(lds + (bufoff) + ldsw + _i * 8192), 16, 0, 0); } while (0)
; #define PG8_LDA(dst, b, h) do { _Pragma("unroll") for (int m = 0; m < 4; ++m) _Pragma("unroll") for (int k = 0; k < 2; ++k) dst[m][k] = *(const PG8_LAS bf16x8*)(lds + PG8_SA(b, h) + aoff + m * 2048 + k * 1024); } while (0)
; #define PG8_LDB(dst, b, h) do { _Pragma("unroll") for (int n = 0; n < 2; ++n) _Pragma("unroll") for (int k = 0; k < 2; ++k) dst[n][k] = *(const PG8_LAS bf16x8*)(lds + PG8_SB(b, h) + boff + n * 2048 + k * 1024); } while (0)
; #define PG8_MMA(ai, bj, At, Bt) do { __builtin_amdgcn_s_setprio(1); _Pragma("unroll") for (int m = 0; m < 4; ++m) _Pragma("unroll") for (int n = 0; n < 2; ++n) _Pragma("unroll") for (int k = 0; k < 2; ++k) \
;         acc[ai][bj][m][n] = __builtin_amdgcn_mfma_f32_16x16x32_bf16(Bt[n][k], At[m][k], acc[ai][bj][m][n], 0, 0, 0); __builtin_amdgcn_s_setprio(0); } while (0)
; #define PG8_WAIT_V(n) asm volatile("s_waitcnt vmcnt(" #n ")" ::: "memory")
; #define PG8_WAIT_L(n) asm volatile("s_waitcnt lgkmcnt(" #n ")" ::: "memory")
; #define PG8_BAR __builtin_amdgcn_s_barrier()
; #define PG8_SCHED __builtin_amdgcn_sched_barrier(0)
; template <class Epi, class Sched, bool ALIGN_EPI = false, bool SP2 = false>
; __device__ __forceinline__ void gemm_phase(PG8_LAS unsigned char* lds, const Gemm g, const Sched& S, const Epi& E) {
;     ...
;             PG8_LDB(B0, 0, 0); PG8_LDB(B1, 0, 1); PG8_SCHED; PG8_LDA(At, 0, 0); PG8_STAGE(PG8_SA(1, 1), a1 + hstep, voffA);
;             PG8_WAIT_V(8); PG8_WAIT_L(0); PG8_BAR; PG8_MMA(0, 0, At, B0); PG8_MMA(0, 1, At, B1); PG8_BAR; PG8_SCHED;
;     ...
;         if constexpr (Epi::ACC_INIT) E.acc_init(ini, nxt);
; #pragma unroll
;         for (int a = 0; a < 2; ++a)
; #pragma unroll
;             for (int b = 0; b < 2; ++b)
; #pragma unroll
;                 for (int m = 0; m < 4; ++m)
; #pragma unroll
;                     for (int n = 0; n < 2; ++n) acc[a][b][m][n] = ini[b][n];
.LBB0_398:
	v_add_u32_e32 v250, 0x10000, v141
	s_add_u32 s60, s60, 0x80
	s_addc_u32 s61, s61, 0
	s_add_u32 s55, s62, 0x100
	s_waitcnt vmcnt(0)
	v_mov_b64_e32 v[18:19], v[2:3]
	v_mov_b64_e32 v[22:23], v[6:7]
	v_mov_b64_e32 v[26:27], v[2:3]
	v_mov_b64_e32 v[30:31], v[6:7]
	v_mov_b64_e32 v[34:35], v[2:3]
	v_mov_b64_e32 v[38:39], v[6:7]
	v_mov_b64_e32 v[74:75], v[10:11]
	v_mov_b64_e32 v[78:79], v[14:15]
	v_mov_b64_e32 v[82:83], v[10:11]
	v_mov_b64_e32 v[86:87], v[14:15]
	v_mov_b64_e32 v[90:91], v[10:11]
	v_mov_b64_e32 v[94:95], v[14:15]
	v_mov_b64_e32 v[42:43], v[2:3]
	v_mov_b64_e32 v[46:47], v[6:7]
	v_mov_b64_e32 v[50:51], v[2:3]
	v_mov_b64_e32 v[54:55], v[6:7]
	v_mov_b64_e32 v[58:59], v[2:3]
	v_mov_b64_e32 v[62:63], v[6:7]
	v_mov_b64_e32 v[66:67], v[2:3]
	v_mov_b64_e32 v[70:71], v[6:7]
	v_mov_b64_e32 v[100:101], v[10:11]
	v_mov_b64_e32 v[104:105], v[14:15]
	v_mov_b64_e32 v[108:109], v[10:11]
	v_mov_b64_e32 v[112:113], v[14:15]
	v_mov_b64_e32 v[116:117], v[10:11]
	v_mov_b64_e32 v[120:121], v[14:15]
	v_mov_b64_e32 v[124:125], v[10:11]
	v_mov_b64_e32 v[128:129], v[14:15]
	s_addc_u32 s73, s63, 0
	s_mov_b32 s62, 0
	v_mov_b64_e32 v[16:17], v[0:1]
	v_mov_b64_e32 v[20:21], v[4:5]
	v_mov_b64_e32 v[24:25], v[0:1]
	v_mov_b64_e32 v[28:29], v[4:5]
	v_mov_b64_e32 v[32:33], v[0:1]
	v_mov_b64_e32 v[36:37], v[4:5]
	v_mov_b64_e32 v[72:73], v[8:9]
	v_mov_b64_e32 v[76:77], v[12:13]
	v_mov_b64_e32 v[80:81], v[8:9]
	v_mov_b64_e32 v[84:85], v[12:13]
	v_mov_b64_e32 v[88:89], v[8:9]
	v_mov_b64_e32 v[92:93], v[12:13]
	v_mov_b64_e32 v[40:41], v[0:1]
	v_mov_b64_e32 v[44:45], v[4:5]
	v_mov_b64_e32 v[48:49], v[0:1]
	v_mov_b64_e32 v[52:53], v[4:5]
	v_mov_b64_e32 v[56:57], v[0:1]
	v_mov_b64_e32 v[60:61], v[4:5]
	v_mov_b64_e32 v[64:65], v[0:1]
	v_mov_b64_e32 v[68:69], v[4:5]
	v_mov_b64_e32 v[98:99], v[8:9]
	v_mov_b64_e32 v[102:103], v[12:13]
	v_mov_b64_e32 v[106:107], v[8:9]
	v_mov_b64_e32 v[110:111], v[12:13]
	v_mov_b64_e32 v[114:115], v[8:9]
	v_mov_b64_e32 v[118:119], v[12:13]
	v_mov_b64_e32 v[122:123], v[8:9]
	v_mov_b64_e32 v[126:127], v[12:13]
.LBB0_399:
	s_add_i32 s74, s62, 2
	ds_read_b128 v[142:145], v250
	ds_read_b128 v[146:149], v250 offset:1024
	ds_read_b128 v[150:153], v250 offset:2048
	ds_read_b128 v[154:157], v250 offset:3072
	ds_read_b128 v[158:161], v250 offset:16384
	ds_read_b128 v[162:165], v250 offset:17408
	ds_read_b128 v[166:169], v250 offset:18432
	ds_read_b128 v[170:173], v250 offset:19456
	s_add_u32 s75, s60, 0x80
	s_addc_u32 s63, s61, 0
	s_cmp_eq_u32 s68, s62
	s_cselect_b32 s62, s40, s75
	s_cselect_b32 s63, s41, s63
	s_cselect_b32 s77, s53, s73
	s_cselect_b32 s76, s52, s55
	s_add_i32 m0, s12, 0xc000
	ds_read_b128 v[174:177], v140
	ds_read_b128 v[178:181], v140 offset:1024
	ds_read_b128 v[182:185], v140 offset:2048
	ds_read_b128 v[186:189], v140 offset:3072
	ds_read_b128 v[190:193], v140 offset:4096
	ds_read_b128 v[202:205], v140 offset:5120
	ds_read_b128 v[206:209], v140 offset:6144
	ds_read_b128 v[230:233], v140 offset:7168
	global_load_lds_dwordx4 v136, s[60:61]
	s_add_i32 m0, s12, 0xe000
	s_nop 0
	global_load_lds_dwordx4 v138, s[60:61]
	s_waitcnt vmcnt(8)
	s_waitcnt lgkmcnt(0)
	s_barrier
	s_setprio 1
	s_waitcnt lgkmcnt(0)
	v_mfma_f32_16x16x32_bf16 v[126:129], v[142:145], v[174:177], v[126:129]
	v_mfma_f32_16x16x32_bf16 v[122:125], v[150:153], v[174:177], v[122:125]
	v_mfma_f32_16x16x32_bf16 v[118:121], v[142:145], v[182:185], v[118:121]
	v_mfma_f32_16x16x32_bf16 v[114:117], v[150:153], v[182:185], v[114:117]
	v_mfma_f32_16x16x32_bf16 v[110:113], v[142:145], v[190:193], v[110:113]
	v_mfma_f32_16x16x32_bf16 v[106:109], v[150:153], v[190:193], v[106:109]
	v_mfma_f32_16x16x32_bf16 v[102:105], v[142:145], v[206:209], v[102:105]
	v_mfma_f32_16x16x32_bf16 v[98:101], v[150:153], v[206:209], v[98:101]
	v_mfma_f32_16x16x32_bf16 v[126:129], v[146:149], v[178:181], v[126:129]
	v_mfma_f32_16x16x32_bf16 v[122:125], v[154:157], v[178:181], v[122:125]
	v_mfma_f32_16x16x32_bf16 v[118:121], v[146:149], v[186:189], v[118:121]
	v_mfma_f32_16x16x32_bf16 v[114:117], v[154:157], v[186:189], v[114:117]
	v_mfma_f32_16x16x32_bf16 v[110:113], v[146:149], v[202:205], v[110:113]
	v_mfma_f32_16x16x32_bf16 v[106:109], v[154:157], v[202:205], v[106:109]
	v_mfma_f32_16x16x32_bf16 v[102:105], v[146:149], v[230:233], v[102:105]
	v_mfma_f32_16x16x32_bf16 v[98:101], v[154:157], v[230:233], v[98:101]
	s_setprio 0
	s_setprio 1
	v_mfma_f32_16x16x32_bf16 v[68:71], v[158:161], v[174:177], v[68:71]
	v_mfma_f32_16x16x32_bf16 v[64:67], v[166:169], v[174:177], v[64:67]
	v_mfma_f32_16x16x32_bf16 v[60:63], v[158:161], v[182:185], v[60:63]
	v_mfma_f32_16x16x32_bf16 v[56:59], v[166:169], v[182:185], v[56:59]
	v_mfma_f32_16x16x32_bf16 v[52:55], v[158:161], v[190:193], v[52:55]
	v_mfma_f32_16x16x32_bf16 v[48:51], v[166:169], v[190:193], v[48:51]
	v_mfma_f32_16x16x32_bf16 v[44:47], v[158:161], v[206:209], v[44:47]
	v_mfma_f32_16x16x32_bf16 v[40:43], v[166:169], v[206:209], v[40:43]
	v_mfma_f32_16x16x32_bf16 v[68:71], v[162:165], v[178:181], v[68:71]
	v_mfma_f32_16x16x32_bf16 v[64:67], v[170:173], v[178:181], v[64:67]
	v_mfma_f32_16x16x32_bf16 v[60:63], v[162:165], v[186:189], v[60:63]
	v_mfma_f32_16x16x32_bf16 v[56:59], v[170:173], v[186:189], v[56:59]
	v_mfma_f32_16x16x32_bf16 v[52:55], v[162:165], v[202:205], v[52:55]
	v_mfma_f32_16x16x32_bf16 v[48:51], v[170:173], v[202:205], v[48:51]
	v_mfma_f32_16x16x32_bf16 v[44:47], v[162:165], v[230:233], v[44:47]
	v_mfma_f32_16x16x32_bf16 v[40:43], v[170:173], v[230:233], v[40:43]
	s_setprio 0
	s_barrier
; #define PG8_STAGE(bufoff, gbase, voff) do { _Pragma("unroll") for (int _i = 0; _i < 2; ++_i) \
;         __builtin_amdgcn_global_load_lds((const unsigned*)((const char*)(gbase) + (voff)[_i]), (PG8_LAS unsigned*)(lds + (bufoff) + ldsw + _i * 8192), 16, 0, 0); } while (0)
; #define PG8_LDA(dst, b, h) do { _Pragma("unroll") for (int m = 0; m < 4; ++m) _Pragma("unroll") for (int k = 0; k < 2; ++k) dst[m][k] = *(const PG8_LAS bf16x8*)(lds + PG8_SA(b, h) + aoff + m * 2048 + k * 1024); } while (0)
; #define PG8_LDB(dst, b, h) do { _Pragma("unroll") for (int n = 0; n < 2; ++n) _Pragma("unroll") for (int k = 0; k < 2; ++k) dst[n][k] = *(const PG8_LAS bf16x8*)(lds + PG8_SB(b, h) + boff + n * 2048 + k * 1024); } while (0)
; #define PG8_MMA(ai, bj, At, Bt) do { __builtin_amdgcn_s_setprio(1); _Pragma("unroll") for (int m = 0; m < 4; ++m) _Pragma("unroll") for (int n = 0; n < 2; ++n) _Pragma("unroll") for (int k = 0; k < 2; ++k) \
;         acc[ai][bj][m][n] = __builtin_amdgcn_mfma_f32_16x16x32_bf16(Bt[n][k], At[m][k], acc[ai][bj][m][n], 0, 0, 0); __builtin_amdgcn_s_setprio(0); } while (0)
; #define PG8_WAIT_V(n) asm volatile("s_waitcnt vmcnt(" #n ")" ::: "memory")
; #define PG8_WAIT_L(n) asm volatile("s_waitcnt lgkmcnt(" #n ")" ::: "memory")
; #define PG8_BAR __builtin_amdgcn_s_barrier()
; #define PG8_SCHED __builtin_amdgcn_sched_barrier(0)
; template <class Epi, class Sched, bool ALIGN_EPI = false, bool SP2 = false>
; __device__ __forceinline__ void gemm_phase(PG8_LAS unsigned char* lds, const Gemm g, const Sched& S, const Epi& E) {
;     ...
;             PG8_LDA(At, 0, 1); PG8_STAGE(PG8_SB(0, 0), b2, voffB); PG8_STAGE(PG8_SB(0, 1), b2 + hstep, voffB); PG8_STAGE(PG8_SA(0, 0), a2, voffA);
;             PG8_WAIT_V(8); PG8_WAIT_L(0); PG8_BAR; PG8_MMA(1, 0, At, B0); PG8_MMA(1, 1, At, B1); PG8_BAR; PG8_SCHED;
;             PG8_LDB(B0, 1, 0); PG8_LDB(B1, 1, 1); PG8_SCHED; PG8_LDA(At, 1, 0); PG8_STAGE(PG8_SA(0, 1), a2 + hstep, voffA);
;             PG8_WAIT_V(8); PG8_WAIT_L(0); PG8_BAR; PG8_MMA(0, 0, At, B0); PG8_MMA(0, 1, At, B1); PG8_BAR; PG8_SCHED;
	s_mov_b32 m0, s13
	ds_read_b128 v[174:177], v140 offset:16384
	ds_read_b128 v[178:181], v140 offset:17408
	ds_read_b128 v[182:185], v140 offset:18432
	ds_read_b128 v[186:189], v140 offset:19456
	ds_read_b128 v[190:193], v140 offset:20480
	ds_read_b128 v[202:205], v140 offset:21504
	ds_read_b128 v[206:209], v140 offset:22528
	ds_read_b128 v[230:233], v140 offset:23552
	global_load_lds_dwordx4 v96, s[76:77]
	s_mov_b32 m0, s16
	s_nop 0
	global_load_lds_dwordx4 v130, s[76:77]
	s_add_u32 s98, s76, s8
	s_addc_u32 s99, s77, s9
	s_add_u32 s76, s76, s42
	s_addc_u32 s77, s77, s43
	s_add_u32 s100, s76, s8
	s_addc_u32 s101, s77, s9
	s_mov_b32 m0, s17
	s_nop 0
	global_load_lds_dwordx4 v96, s[76:77]
	s_mov_b32 m0, s20
	s_nop 0
	global_load_lds_dwordx4 v130, s[76:77]
	s_mov_b32 m0, s12
	s_nop 0
	global_load_lds_dwordx4 v134, s[62:63]
	s_mov_b32 m0, s21
	s_nop 0
	global_load_lds_dwordx4 v132, s[62:63]
	s_waitcnt vmcnt(8)
	s_waitcnt lgkmcnt(0)
	s_barrier
	s_setprio 1
	s_waitcnt lgkmcnt(0)
	v_mfma_f32_16x16x32_bf16 v[92:95], v[142:145], v[174:177], v[92:95]
	v_mfma_f32_16x16x32_bf16 v[88:91], v[150:153], v[174:177], v[88:91]
	v_mfma_f32_16x16x32_bf16 v[84:87], v[142:145], v[182:185], v[84:87]
	v_mfma_f32_16x16x32_bf16 v[80:83], v[150:153], v[182:185], v[80:83]
	v_mfma_f32_16x16x32_bf16 v[76:79], v[142:145], v[190:193], v[76:79]
	v_mfma_f32_16x16x32_bf16 v[72:75], v[150:153], v[190:193], v[72:75]
	v_mfma_f32_16x16x32_bf16 v[12:15], v[142:145], v[206:209], v[12:15]
	v_mfma_f32_16x16x32_bf16 v[8:11], v[150:153], v[206:209], v[8:11]
	v_mfma_f32_16x16x32_bf16 v[92:95], v[146:149], v[178:181], v[92:95]
	v_mfma_f32_16x16x32_bf16 v[88:91], v[154:157], v[178:181], v[88:91]
	v_mfma_f32_16x16x32_bf16 v[84:87], v[146:149], v[186:189], v[84:87]
	v_mfma_f32_16x16x32_bf16 v[80:83], v[154:157], v[186:189], v[80:83]
	v_mfma_f32_16x16x32_bf16 v[76:79], v[146:149], v[202:205], v[76:79]
	v_mfma_f32_16x16x32_bf16 v[72:75], v[154:157], v[202:205], v[72:75]
	v_mfma_f32_16x16x32_bf16 v[12:15], v[146:149], v[230:233], v[12:15]
	v_mfma_f32_16x16x32_bf16 v[8:11], v[154:157], v[230:233], v[8:11]
	s_setprio 0
	s_setprio 1
	v_mfma_f32_16x16x32_bf16 v[36:39], v[158:161], v[174:177], v[36:39]
	v_mfma_f32_16x16x32_bf16 v[32:35], v[166:169], v[174:177], v[32:35]
	v_mfma_f32_16x16x32_bf16 v[28:31], v[158:161], v[182:185], v[28:31]
	v_mfma_f32_16x16x32_bf16 v[24:27], v[166:169], v[182:185], v[24:27]
	v_mfma_f32_16x16x32_bf16 v[20:23], v[158:161], v[190:193], v[20:23]
	v_mfma_f32_16x16x32_bf16 v[16:19], v[166:169], v[190:193], v[16:19]
	v_mfma_f32_16x16x32_bf16 v[4:7], v[158:161], v[206:209], v[4:7]
	v_mfma_f32_16x16x32_bf16 v[0:3], v[166:169], v[206:209], v[0:3]
	v_mfma_f32_16x16x32_bf16 v[36:39], v[162:165], v[178:181], v[36:39]
	v_mfma_f32_16x16x32_bf16 v[32:35], v[170:173], v[178:181], v[32:35]
	v_mfma_f32_16x16x32_bf16 v[28:31], v[162:165], v[186:189], v[28:31]
	v_mfma_f32_16x16x32_bf16 v[24:27], v[170:173], v[186:189], v[24:27]
	v_mfma_f32_16x16x32_bf16 v[20:23], v[162:165], v[202:205], v[20:23]
	v_mfma_f32_16x16x32_bf16 v[16:19], v[170:173], v[202:205], v[16:19]
	v_mfma_f32_16x16x32_bf16 v[4:7], v[162:165], v[230:233], v[4:7]
	v_mfma_f32_16x16x32_bf16 v[0:3], v[170:173], v[230:233], v[0:3]
	s_setprio 0
	s_barrier
	ds_read_b128 v[142:145], v250 offset:32768
	ds_read_b128 v[146:149], v250 offset:33792
	ds_read_b128 v[150:153], v250 offset:34816
	ds_read_b128 v[154:157], v250 offset:35840
	ds_read_b128 v[158:161], v250 offset:49152
	ds_read_b128 v[162:165], v250 offset:50176
	ds_read_b128 v[166:169], v250 offset:51200
	ds_read_b128 v[170:173], v250 offset:52224
	s_add_u32 s62, s62, s42
	s_addc_u32 s63, s63, s43
	s_mov_b32 m0, s22
	ds_read_b128 v[174:177], v140 offset:32768
	ds_read_b128 v[178:181], v140 offset:33792
	ds_read_b128 v[182:185], v140 offset:34816
	ds_read_b128 v[186:189], v140 offset:35840
	ds_read_b128 v[190:193], v140 offset:36864
	ds_read_b128 v[202:205], v140 offset:37888
	ds_read_b128 v[206:209], v140 offset:38912
	ds_read_b128 v[230:233], v140 offset:39936
	global_load_lds_dwordx4 v134, s[62:63]
	s_mov_b32 m0, s23
	s_nop 0
	global_load_lds_dwordx4 v132, s[62:63]
	s_waitcnt vmcnt(8)
	s_waitcnt lgkmcnt(0)
	s_barrier
; #define PG8_STAGE(bufoff, gbase, voff) do { _Pragma("unroll") for (int _i = 0; _i < 2; ++_i) \
;         __builtin_amdgcn_global_load_lds((const unsigned*)((const char*)(gbase) + (voff)[_i]), (PG8_LAS unsigned*)(lds + (bufoff) + ldsw + _i * 8192), 16, 0, 0); } while (0)
; #define PG8_LDA(dst, b, h) do { _Pragma("unroll") for (int m = 0; m < 4; ++m) _Pragma("unroll") for (int k = 0; k < 2; ++k) dst[m][k] = *(const PG8_LAS bf16x8*)(lds + PG8_SA(b, h) + aoff + m * 2048 + k * 1024); } while (0)
; #define PG8_MMA(ai, bj, At, Bt) do { __builtin_amdgcn_s_setprio(1); _Pragma("unroll") for (int m = 0; m < 4; ++m) _Pragma("unroll") for (int n = 0; n < 2; ++n) _Pragma("unroll") for (int k = 0; k < 2; ++k) \
;         acc[ai][bj][m][n] = __builtin_amdgcn_mfma_f32_16x16x32_bf16(Bt[n][k], At[m][k], acc[ai][bj][m][n], 0, 0, 0); __builtin_amdgcn_s_setprio(0); } while (0)
; #define PG8_WAIT_V(n) asm volatile("s_waitcnt vmcnt(" #n ")" ::: "memory")
; #define PG8_WAIT_L(n) asm volatile("s_waitcnt lgkmcnt(" #n ")" ::: "memory")
; #define PG8_BAR __builtin_amdgcn_s_barrier()
; #define PG8_SCHED __builtin_amdgcn_sched_barrier(0)
; template <class Epi, class Sched, bool ALIGN_EPI = false, bool SP2 = false>
; __device__ __forceinline__ void gemm_phase(PG8_LAS unsigned char* lds, const Gemm g, const Sched& S, const Epi& E) {
;     ...
;             PG8_WAIT_V(8); PG8_WAIT_L(0); PG8_BAR; PG8_MMA(0, 0, At, B0); PG8_MMA(0, 1, At, B1); PG8_BAR; PG8_SCHED;
;             PG8_LDA(At, 1, 1); PG8_STAGE(PG8_SB(1, 0), b3, voffB); PG8_STAGE(PG8_SB(1, 1), b3 + hstep, voffB); PG8_STAGE(PG8_SA(1, 0), a3, voffA);
;             PG8_WAIT_V(8); PG8_WAIT_L(0); PG8_BAR; PG8_MMA(1, 0, At, B0); PG8_MMA(1, 1, At, B1); PG8_BAR; PG8_SCHED;
	s_setprio 1
	s_waitcnt lgkmcnt(0)
	v_mfma_f32_16x16x32_bf16 v[126:129], v[142:145], v[174:177], v[126:129]
	v_mfma_f32_16x16x32_bf16 v[122:125], v[150:153], v[174:177], v[122:125]
	v_mfma_f32_16x16x32_bf16 v[118:121], v[142:145], v[182:185], v[118:121]
	v_mfma_f32_16x16x32_bf16 v[114:117], v[150:153], v[182:185], v[114:117]
	v_mfma_f32_16x16x32_bf16 v[110:113], v[142:145], v[190:193], v[110:113]
	v_mfma_f32_16x16x32_bf16 v[106:109], v[150:153], v[190:193], v[106:109]
	v_mfma_f32_16x16x32_bf16 v[102:105], v[142:145], v[206:209], v[102:105]
	v_mfma_f32_16x16x32_bf16 v[98:101], v[150:153], v[206:209], v[98:101]
	v_mfma_f32_16x16x32_bf16 v[126:129], v[146:149], v[178:181], v[126:129]
	v_mfma_f32_16x16x32_bf16 v[122:125], v[154:157], v[178:181], v[122:125]
	v_mfma_f32_16x16x32_bf16 v[118:121], v[146:149], v[186:189], v[118:121]
	v_mfma_f32_16x16x32_bf16 v[114:117], v[154:157], v[186:189], v[114:117]
	v_mfma_f32_16x16x32_bf16 v[110:113], v[146:149], v[202:205], v[110:113]
	v_mfma_f32_16x16x32_bf16 v[106:109], v[154:157], v[202:205], v[106:109]
	v_mfma_f32_16x16x32_bf16 v[102:105], v[146:149], v[230:233], v[102:105]
	v_mfma_f32_16x16x32_bf16 v[98:101], v[154:157], v[230:233], v[98:101]
	s_setprio 0
	s_setprio 1
	v_mfma_f32_16x16x32_bf16 v[68:71], v[158:161], v[174:177], v[68:71]
	v_mfma_f32_16x16x32_bf16 v[64:67], v[166:169], v[174:177], v[64:67]
	v_mfma_f32_16x16x32_bf16 v[60:63], v[158:161], v[182:185], v[60:63]
	v_mfma_f32_16x16x32_bf16 v[56:59], v[166:169], v[182:185], v[56:59]
	v_mfma_f32_16x16x32_bf16 v[52:55], v[158:161], v[190:193], v[52:55]
	v_mfma_f32_16x16x32_bf16 v[48:51], v[166:169], v[190:193], v[48:51]
	v_mfma_f32_16x16x32_bf16 v[44:47], v[158:161], v[206:209], v[44:47]
	v_mfma_f32_16x16x32_bf16 v[40:43], v[166:169], v[206:209], v[40:43]
	v_mfma_f32_16x16x32_bf16 v[68:71], v[162:165], v[178:181], v[68:71]
	v_mfma_f32_16x16x32_bf16 v[64:67], v[170:173], v[178:181], v[64:67]
	v_mfma_f32_16x16x32_bf16 v[60:63], v[162:165], v[186:189], v[60:63]
	v_mfma_f32_16x16x32_bf16 v[56:59], v[170:173], v[186:189], v[56:59]
	v_mfma_f32_16x16x32_bf16 v[52:55], v[162:165], v[202:205], v[52:55]
	v_mfma_f32_16x16x32_bf16 v[48:51], v[170:173], v[202:205], v[48:51]
	v_mfma_f32_16x16x32_bf16 v[44:47], v[162:165], v[230:233], v[44:47]
	v_mfma_f32_16x16x32_bf16 v[40:43], v[170:173], v[230:233], v[40:43]
	s_setprio 0
	s_barrier
	s_mov_b32 m0, s31
	ds_read_b128 v[174:177], v140 offset:49152
	ds_read_b128 v[178:181], v140 offset:50176
	ds_read_b128 v[182:185], v140 offset:51200
	ds_read_b128 v[186:189], v140 offset:52224
	ds_read_b128 v[190:193], v140 offset:53248
	ds_read_b128 v[202:205], v140 offset:54272
	ds_read_b128 v[206:209], v140 offset:55296
	ds_read_b128 v[230:233], v140 offset:56320
	global_load_lds_dwordx4 v96, s[98:99]
	s_mov_b32 m0, s34
	s_nop 0
	global_load_lds_dwordx4 v130, s[98:99]
	s_mov_b32 m0, s65
	s_nop 0
	global_load_lds_dwordx4 v96, s[100:101]
	s_mov_b32 m0, s66
	s_nop 0
	global_load_lds_dwordx4 v130, s[100:101]
	s_sub_u32 s98, s62, s42
	s_subb_u32 s99, s63, s43
	s_add_u32 s98, s98, s8
	s_addc_u32 s99, s99, s9
	s_mov_b32 m0, s36
	s_nop 0
	global_load_lds_dwordx4 v134, s[98:99]
	s_mov_b32 m0, s64
	s_nop 0
	global_load_lds_dwordx4 v132, s[98:99]
	s_waitcnt vmcnt(8)
	s_waitcnt lgkmcnt(0)
	s_barrier
	s_setprio 1
	s_waitcnt lgkmcnt(0)
	v_mfma_f32_16x16x32_bf16 v[92:95], v[142:145], v[174:177], v[92:95]
	v_mfma_f32_16x16x32_bf16 v[88:91], v[150:153], v[174:177], v[88:91]
	v_mfma_f32_16x16x32_bf16 v[84:87], v[142:145], v[182:185], v[84:87]
	v_mfma_f32_16x16x32_bf16 v[80:83], v[150:153], v[182:185], v[80:83]
	v_mfma_f32_16x16x32_bf16 v[76:79], v[142:145], v[190:193], v[76:79]
	v_mfma_f32_16x16x32_bf16 v[72:75], v[150:153], v[190:193], v[72:75]
	v_mfma_f32_16x16x32_bf16 v[12:15], v[142:145], v[206:209], v[12:15]
	v_mfma_f32_16x16x32_bf16 v[8:11], v[150:153], v[206:209], v[8:11]
	v_mfma_f32_16x16x32_bf16 v[92:95], v[146:149], v[178:181], v[92:95]
	v_mfma_f32_16x16x32_bf16 v[88:91], v[154:157], v[178:181], v[88:91]
	v_mfma_f32_16x16x32_bf16 v[84:87], v[146:149], v[186:189], v[84:87]
	v_mfma_f32_16x16x32_bf16 v[80:83], v[154:157], v[186:189], v[80:83]
	v_mfma_f32_16x16x32_bf16 v[76:79], v[146:149], v[202:205], v[76:79]
	v_mfma_f32_16x16x32_bf16 v[72:75], v[154:157], v[202:205], v[72:75]
	v_mfma_f32_16x16x32_bf16 v[12:15], v[146:149], v[230:233], v[12:15]
	v_mfma_f32_16x16x32_bf16 v[8:11], v[154:157], v[230:233], v[8:11]
	s_setprio 0
	s_setprio 1
	v_mfma_f32_16x16x32_bf16 v[36:39], v[158:161], v[174:177], v[36:39]
	v_mfma_f32_16x16x32_bf16 v[32:35], v[166:169], v[174:177], v[32:35]
	v_mfma_f32_16x16x32_bf16 v[28:31], v[158:161], v[182:185], v[28:31]
	v_mfma_f32_16x16x32_bf16 v[24:27], v[166:169], v[182:185], v[24:27]
	v_mfma_f32_16x16x32_bf16 v[20:23], v[158:161], v[190:193], v[20:23]
	v_mfma_f32_16x16x32_bf16 v[16:19], v[166:169], v[190:193], v[16:19]
	v_mfma_f32_16x16x32_bf16 v[4:7], v[158:161], v[206:209], v[4:7]
	v_mfma_f32_16x16x32_bf16 v[0:3], v[166:169], v[206:209], v[0:3]
	v_mfma_f32_16x16x32_bf16 v[36:39], v[162:165], v[178:181], v[36:39]
	v_mfma_f32_16x16x32_bf16 v[32:35], v[170:173], v[178:181], v[32:35]
	v_mfma_f32_16x16x32_bf16 v[28:31], v[162:165], v[186:189], v[28:31]
	v_mfma_f32_16x16x32_bf16 v[24:27], v[170:173], v[186:189], v[24:27]
	v_mfma_f32_16x16x32_bf16 v[20:23], v[162:165], v[202:205], v[20:23]
	v_mfma_f32_16x16x32_bf16 v[16:19], v[170:173], v[202:205], v[16:19]
	v_mfma_f32_16x16x32_bf16 v[4:7], v[162:165], v[230:233], v[4:7]
	v_mfma_f32_16x16x32_bf16 v[0:3], v[170:173], v[230:233], v[0:3]
	s_setprio 0
	s_barrier
	s_add_u32 s60, s60, 0x100
	s_addc_u32 s61, s61, 0
	s_add_u32 s55, s55, 0x100
	s_addc_u32 s73, s73, 0
	s_cmp_ge_i32 s74, s67
	s_mov_b32 s62, s74
	s_cbranch_scc0 .LBB0_399
	s_and_b64 vcc, exec, s[50:51]
	s_cbranch_vccz .LBB0_410
